# attention: pair 1 also staged by LDS-DMA (no initial wait on register-staged loads)
# speedup vs baseline: 1.0188x; 1.0021x over previous
; DEV int vbsel() { return __builtin_amdgcn_readfirstlane((int)(threadIdx.x >> 8)); }
; #define ALOAD(kt) { const int key0_ = (kt) * 128; \
;     if (kc < 12) { _Pragma("unroll") for (int i = 0; i < 4; ++i) kr[i] = *(const u32x4*)(Kb + (size_t)(key0_ + krow + 32 * i) * 96 + kc * 8); } \
;     _Pragma("unroll") for (int i = 0; i < 2; ++i) vr[i] = *(const u32x4*)(Vt + (size_t)vrow * NKEY + key0_ + i * 64 + vc * 8); }
; #define ASTORE(slot) { char* sk_ = smem + (slot) * KB; char* sv_ = smem + (slot) * VB; \
;     if (kc < 12) { _Pragma("unroll") for (int i = 0; i < 4; ++i) *(u32x4*)(sk_ + kwo + i * 8192) = kr[i]; } \
;     _Pragma("unroll") for (int i = 0; i < 2; ++i) *(u32x4*)(sv_ + vwo + i * VB) = vr[i]; }
; #define PVLOAD(slot) { const char* s = smem + (slot) * VB; \
;     _Pragma("unroll") for (int vt = 0; vt < 4; ++vt) vf[0][vt] = *(const bf16x8*)(s + vt * 2048 + vro + (((0 * 4 + lq) ^ (l15 >> 1)) << 4)); }
; #define ABAR() { asm volatile("s_waitcnt lgkmcnt(0)" ::: "memory"); __builtin_amdgcn_s_barrier(); asm volatile("" ::: "memory"); }
; DEV void attn_item(const P& p, int bh, int qrow0, int nkt, int outrow0, char* smem) {
;     ...
;   const bool skew = vbsel() != 0;
;   asm volatile("" : "+s"(nkt));
;     ...
;   const int npair = nkt >> 1;
;   ALOAD(0); ASTORE(0); if (npair > 1) ALOAD(1); ABAR();
;   int s0 = 0;
; #pragma nounroll
;   for (int kp = 0; kp < npair; ++kp) {
;     const int sn = (s0 == 4) ? 0 : s0 + 2;
;     if (kp + 1 < npair) ASTORE(sn);
;     if (kp + 2 < npair) ALOAD(kp + 2);
;     if (!skew) {
;       QK(s0); PVLOAD(s0); __builtin_amdgcn_sched_barrier(0); SM(kp == 0); PVMMA(s0);
.LBB0_158:
	s_waitcnt lgkmcnt(0)
	s_barrier
	s_cmpk_gt_u32 s6, 0xff
	v_lshrrev_b32_e32 v1, 1, v207
	v_lshl_add_u32 v210, v207, 7, v4
	s_cselect_b64 s[4:5], -1, 0
	s_cmp_lt_i32 s23, 1
	v_xor_b32_e32 v211, v206, v1
	v_bitop3_b32 v208, v206, v1, 4 bitop3:0x36
	s_cbranch_scc1 .LBB0_214
	v_mov_b32_e32 v1, v41
	v_lshl_add_u64 v[204:205], s[2:3], 0, v[0:1]
	v_xor_b32_e32 v0, v206, v207
	v_lshlrev_b32_e32 v217, 4, v0
	v_bitop3_b32 v0, v206, v207, 4 bitop3:0x36
	v_mov_b32_e32 v42, v41
	v_mov_b32_e32 v43, v41
	v_lshlrev_b32_e32 v218, 4, v0
	v_bitop3_b32 v0, v206, v207, 8 bitop3:0x36
	v_mov_b32_e32 v40, v41
	v_mov_b32_e32 v221, 0
	v_mov_b64_e32 v[94:95], v[42:43]
	v_mov_b64_e32 v[98:99], v[42:43]
	v_mov_b64_e32 v[102:103], v[42:43]
	v_mov_b64_e32 v[106:107], v[42:43]
	v_mov_b64_e32 v[110:111], v[42:43]
	v_mov_b64_e32 v[114:115], v[42:43]
	v_mov_b64_e32 v[118:119], v[42:43]
	v_mov_b64_e32 v[122:123], v[42:43]
	v_lshl_add_u32 v214, v207, 8, v2
	v_lshlrev_b32_e32 v215, 4, v211
	v_lshlrev_b32_e32 v216, 4, v208
	v_lshlrev_b32_e32 v219, 4, v0
	s_mov_b32 s25, 0
	v_mov_b32_e32 v220, 0
	v_mov_b64_e32 v[92:93], v[40:41]
	v_mov_b64_e32 v[96:97], v[40:41]
	v_mov_b64_e32 v[100:101], v[40:41]
	v_mov_b64_e32 v[104:105], v[40:41]
	v_mov_b64_e32 v[108:109], v[40:41]
	v_mov_b64_e32 v[112:113], v[40:41]
	v_mov_b64_e32 v[116:117], v[40:41]
	v_mov_b64_e32 v[120:121], v[40:41]
	s_mov_b32 s10, 0
	s_mov_b32 s11, 0
	v_mov_b32_e32 v0, 0
	v_mov_b32_e32 v1, v221
	v_mov_b32_e32 v2, v221
	v_mov_b32_e32 v3, v221
	v_mov_b32_e32 v4, v221
	v_mov_b32_e32 v5, v221
	v_mov_b32_e32 v6, v221
	v_mov_b32_e32 v7, v221
	v_xor_b32_e32 v226, 0x80000000, v221
	v_xor_b32_e32 v230, 0x80000000, v220
	v_mov_b32_e32 v222, s56
	v_mov_b32_e32 v227, v226
	v_mov_b32_e32 v231, v230
	v_mov_b32_e32 v223, v222
	v_mov_b32_e32 v228, v226
	v_mov_b32_e32 v232, v230
	v_mov_b32_e32 v224, v222
	v_mov_b32_e32 v229, v226
	v_mov_b32_e32 v233, v230
	v_mov_b32_e32 v225, v222
	v_lshrrev_b32_e32 v8, 6, v201
	v_and_b32_e32 v9, 15, v237
	v_lshrrev_b32_e32 v10, 4, v237
	v_readfirstlane_b32 s2, v8
	s_lshl_b32 s40, s2, 12
	s_lshl_b32 s41, s2, 10
	v_lshl_add_u32 v11, v8, 4, v10
	v_add_u32_e32 v36, 0, v10
	v_xor_b32_e32 v36, v36, v9
	v_add_u32_e32 v37, 0, v11
	v_mul_u32_u24_e32 v37, 0xc0, v37
	v_lshl_add_u32 v13, v36, 4, v37
	v_add_u32_e32 v36, 4, v10
	v_xor_b32_e32 v36, v36, v9
	v_add_u32_e32 v37, 4, v11
	v_mul_u32_u24_e32 v37, 0xc0, v37
	v_lshl_add_u32 v14, v36, 4, v37
	v_add_u32_e32 v36, 8, v10
	v_xor_b32_e32 v36, v36, v9
	v_add_u32_e32 v37, 8, v11
	v_mul_u32_u24_e32 v37, 0xc0, v37
	v_lshl_add_u32 v15, v36, 4, v37
	v_add_u32_e32 v36, 12, v10
	v_xor_b32_e32 v36, v36, v9
	v_add_u32_e32 v37, 12, v11
	v_mul_u32_u24_e32 v37, 0xc0, v37
	v_lshl_add_u32 v12, v36, 4, v37
	v_lshrrev_b32_e32 v36, 3, v237
	v_lshl_add_u32 v36, v8, 3, v36
	v_bfe_u32 v37, v36, 1, 3
	v_and_b32_e32 v10, 7, v237
	v_xor_b32_e32 v37, v37, v10
	v_mul_u32_u24_e32 v36, 0x2200, v36
	v_lshl_add_u32 v234, v37, 4, v36
	s_mul_i32 s6, s19, 0xcc000
	s_mul_hi_i32 s7, s19, 0xcc000
	s_add_u32 s6, s14, s6
	s_addc_u32 s7, s15, s7
	s_add_u32 s6, s6, 0x6000
	s_addc_u32 s7, s7, 0
	s_mul_i32 s8, s19, 0x88000
	s_mul_hi_i32 s9, s19, 0x88000
	s_add_u32 s8, s16, s8
	s_addc_u32 s9, s17, s9
	s_add_u32 s8, s8, 0x100
	s_addc_u32 s9, s9, 0
	s_cmp_lt_i32 s23, 2
	s_cbranch_scc1 .Latt_loop
	s_mov_b32 s2, 2
	s_lshl_b32 s3, s2, 14
	s_add_i32 s3, s3, s40
	s_add_i32 m0, s3, 0x0
	s_nop 0
	global_load_lds_dwordx4 v13, s[6:7]
	s_add_i32 m0, s3, 0x400
	s_nop 0
	global_load_lds_dwordx4 v14, s[6:7]
	s_add_i32 m0, s3, 0x800
	s_nop 0
	global_load_lds_dwordx4 v15, s[6:7]
	s_add_i32 m0, s3, 0xc00
	s_nop 0
	global_load_lds_dwordx4 v12, s[6:7]
	s_lshl_b32 s3, s2, 13
	s_add_i32 s3, s3, s41
	s_add_i32 s3, s3, 0x18000
	v_add_u32_e32 v9, 0x80, v234
	s_mov_b32 m0, s3
	s_nop 0
	global_load_lds_dwordx4 v234, s[8:9]
	s_add_i32 m0, s3, 0x2000
	s_nop 0
	global_load_lds_dwordx4 v9, s[8:9]
	s_add_u32 s6, s6, 0x6000
	s_addc_u32 s7, s7, 0
	s_add_u32 s8, s8, 0x100
	s_addc_u32 s9, s9, 0
.Latt_loop:
	s_add_i32 s2, s10, 2
	s_cmp_lg_u32 s10, 4
	s_cselect_b32 s24, s2, 0
	s_add_i32 s26, s11, 1
	s_add_i32 s2, s11, 2
	s_cmp_ge_i32 s2, s23
	s_cbranch_scc1 .Latt_nodma
	s_add_i32 s2, s24, 2
	s_cmp_lg_u32 s24, 4
	s_cselect_b32 s2, s2, 0
	s_lshl_b32 s3, s2, 14
	s_add_i32 s3, s3, s40
	s_add_i32 m0, s3, 0x0
	s_nop 0
	global_load_lds_dwordx4 v13, s[6:7]
	s_add_i32 m0, s3, 0x400
	s_nop 0
	global_load_lds_dwordx4 v14, s[6:7]
	s_add_i32 m0, s3, 0x800
	s_nop 0
	global_load_lds_dwordx4 v15, s[6:7]
	s_add_i32 m0, s3, 0xc00
	s_nop 0
	global_load_lds_dwordx4 v12, s[6:7]
	s_lshl_b32 s3, s2, 13
	s_add_i32 s3, s3, s41
	s_add_i32 s3, s3, 0x18000
	v_add_u32_e32 v9, 0x80, v234
	s_mov_b32 m0, s3
	s_nop 0
	global_load_lds_dwordx4 v234, s[8:9]
	s_add_i32 m0, s3, 0x2000
	s_nop 0
	global_load_lds_dwordx4 v9, s[8:9]
	s_add_u32 s6, s6, 0x6000
	s_addc_u32 s7, s7, 0
	s_add_u32 s8, s8, 0x100
	s_addc_u32 s9, s9, 0

.Latt_r0_a:
	v_xor_b32_e32 v10, 16, v237
	v_lshlrev_b32_e32 v10, 2, v10
	ds_bpermute_b32 v10, v10, v36
	v_xor_b32_e32 v9, 32, v237
	v_lshlrev_b32_e32 v9, 2, v9
	v_max_f32_e32 v11, v36, v36
	s_waitcnt lgkmcnt(0)
	v_max_f32_e32 v10, v10, v10
	v_max_f32_e32 v11, v11, v10
	s_nop 0
	ds_bpermute_b32 v10, v9, v11
	s_waitcnt lgkmcnt(0)
	v_max_f32_e32 v10, v10, v10
	v_max_f32_e32 v11, v11, v10
	v_exp_f32_e64 v8, -v11
	v_add_f32_e32 v221, v221, v11
	v_xor_b32_e32 v226, 0x80000000, v221
	v_sub_f32_e32 v140, v140, v11
	v_sub_f32_e32 v141, v141, v11
	v_sub_f32_e32 v142, v142, v11
	v_sub_f32_e32 v143, v143, v11
	v_sub_f32_e32 v144, v144, v11
	v_sub_f32_e32 v145, v145, v11
	v_sub_f32_e32 v146, v146, v11
	v_sub_f32_e32 v147, v147, v11
	v_sub_f32_e32 v148, v148, v11
	v_sub_f32_e32 v149, v149, v11
	v_sub_f32_e32 v150, v150, v11
	v_sub_f32_e32 v151, v151, v11
	v_sub_f32_e32 v152, v152, v11
	v_sub_f32_e32 v153, v153, v11
	v_sub_f32_e32 v154, v154, v11
	v_sub_f32_e32 v155, v155, v11
	v_mov_b32_e32 v227, v226
	v_mov_b32_e32 v228, v226
	v_mov_b32_e32 v229, v226
	v_pk_mul_f32 v[92:93], v[92:93], v[8:9] op_sel_hi:[1,0]
	v_pk_mul_f32 v[94:95], v[94:95], v[8:9] op_sel_hi:[1,0]
	v_pk_mul_f32 v[100:101], v[100:101], v[8:9] op_sel_hi:[1,0]
	v_pk_mul_f32 v[102:103], v[102:103], v[8:9] op_sel_hi:[1,0]
	v_pk_mul_f32 v[108:109], v[108:109], v[8:9] op_sel_hi:[1,0]
	v_pk_mul_f32 v[110:111], v[110:111], v[8:9] op_sel_hi:[1,0]
	v_pk_mul_f32 v[116:117], v[116:117], v[8:9] op_sel_hi:[1,0]
	v_pk_mul_f32 v[118:119], v[118:119], v[8:9] op_sel_hi:[1,0]
	v_pk_mul_f32 v[0:1], v[0:1], v[8:9] op_sel_hi:[1,0]
	v_pk_mul_f32 v[2:3], v[2:3], v[8:9] op_sel_hi:[1,0]

.Latt_r1_a:
	v_xor_b32_e32 v10, 16, v237
	v_lshlrev_b32_e32 v10, 2, v10
	ds_bpermute_b32 v10, v10, v37
	v_xor_b32_e32 v9, 32, v237
	v_lshlrev_b32_e32 v9, 2, v9
	v_max_f32_e32 v11, v37, v37
	s_waitcnt lgkmcnt(0)
	v_max_f32_e32 v10, v10, v10
	v_max_f32_e32 v11, v11, v10
	s_nop 0
	ds_bpermute_b32 v10, v9, v11
	s_waitcnt lgkmcnt(0)
	v_max_f32_e32 v10, v10, v10
	v_max_f32_e32 v11, v11, v10
	v_exp_f32_e64 v8, -v11
	v_add_f32_e32 v220, v220, v11
	v_xor_b32_e32 v230, 0x80000000, v220
	v_sub_f32_e32 v124, v124, v11
	v_sub_f32_e32 v125, v125, v11
	v_sub_f32_e32 v126, v126, v11
	v_sub_f32_e32 v127, v127, v11
	v_sub_f32_e32 v128, v128, v11
	v_sub_f32_e32 v129, v129, v11
	v_sub_f32_e32 v130, v130, v11
	v_sub_f32_e32 v131, v131, v11
	v_sub_f32_e32 v132, v132, v11
	v_sub_f32_e32 v133, v133, v11
	v_sub_f32_e32 v134, v134, v11
	v_sub_f32_e32 v135, v135, v11
	v_sub_f32_e32 v136, v136, v11
	v_sub_f32_e32 v137, v137, v11
	v_sub_f32_e32 v138, v138, v11
	v_sub_f32_e32 v139, v139, v11
	v_mov_b32_e32 v231, v230
	v_mov_b32_e32 v232, v230
	v_mov_b32_e32 v233, v230
	v_pk_mul_f32 v[96:97], v[96:97], v[8:9] op_sel_hi:[1,0]
	v_pk_mul_f32 v[98:99], v[98:99], v[8:9] op_sel_hi:[1,0]
	v_pk_mul_f32 v[104:105], v[104:105], v[8:9] op_sel_hi:[1,0]
	v_pk_mul_f32 v[106:107], v[106:107], v[8:9] op_sel_hi:[1,0]
	v_pk_mul_f32 v[112:113], v[112:113], v[8:9] op_sel_hi:[1,0]
	v_pk_mul_f32 v[114:115], v[114:115], v[8:9] op_sel_hi:[1,0]
	v_pk_mul_f32 v[120:121], v[120:121], v[8:9] op_sel_hi:[1,0]
	v_pk_mul_f32 v[122:123], v[122:123], v[8:9] op_sel_hi:[1,0]
	v_pk_mul_f32 v[4:5], v[4:5], v[8:9] op_sel_hi:[1,0]
	v_pk_mul_f32 v[6:7], v[6:7], v[8:9] op_sel_hi:[1,0]
	s_branch .Latt_c_a
